# banded mode-2: next item's Q / sink / first K,V tile prefetched in the current item's last tile (section 7.10 inside the persistent item loop), v61 + pf
# speedup vs baseline: 1.0437x; 1.0017x over previous
.LBB0_895:
	s_or_b64 exec, exec, s[0:1]
	s_and_b64 vcc, exec, s[10:11]
	s_waitcnt lgkmcnt(0)
	s_barrier
	s_cbranch_vccz .LBB0_910
	v_readlane_b32 s0, v255, 29
	s_cmp_lg_u32 s0, 1
	s_mov_b64 s[0:1], -1
	s_mov_b32 s8, 0xc2fc0000
	s_cbranch_scc0 .LBB0_912
	s_mov_b64 s[42:43], s[76:77]
	s_mov_b64 s[38:39], s[76:77]
	s_mov_b64 s[40:41], s[76:77]
	s_mov_b64 s[0:1], s[76:77]
	s_mov_b64 s[4:5], s[76:77]
	v_mov_b32_e32 v0, v239
	v_readlane_b32 s4, v254, 24
	v_readlane_b32 s5, v254, 25
	s_andn2_b64 vcc, exec, s[4:5]
	s_cbranch_vccnz .LBB0_911
	v_ashrrev_i32_e32 v1, 5, v0
	v_lshlrev_b32_e32 v2, 3, v1
	v_ashrrev_i32_e32 v3, 31, v2
	v_lshl_add_u64 v[2:3], v[2:3], 1, s[42:43]
	s_mov_b64 s[4:5], 0xa000000
	v_lshl_add_u64 v[180:181], v[2:3], 0, s[4:5]
	v_lshlrev_b32_e32 v2, 4, v0
	v_ashrrev_i32_e32 v3, 31, v2
	v_lshlrev_b32_e32 v202, 2, v1
	v_and_b32_e32 v1, 64, v238
	v_and_b32_e32 v178, 31, v0
	v_lshl_add_u64 v[4:5], s[38:39], 0, v[2:3]
	s_mov_b64 s[4:5], 0xe800000
	v_cmp_gt_u32_e32 vcc, 32, v0
	v_xor_b32_e32 v0, 32, v238
	v_add_u32_e32 v1, 64, v1
	v_lshl_add_u64 v[182:183], v[4:5], 0, s[4:5]
	v_lshl_add_u64 v[2:3], s[40:41], 0, v[2:3]
	s_mov_b64 s[4:5], 0x10001000
	v_cndmask_b32_e64 v179, 0, 1.0, vcc
	v_cmp_lt_i32_e32 vcc, v0, v1
	s_add_u32 s0, s0, 0x11800000
	v_lshl_add_u64 v[184:185], v[2:3], 0, s[4:5]
	v_cndmask_b32_e32 v0, v238, v0, vcc
	v_readlane_b32 s4, v253, 20
	s_addc_u32 s1, s1, 0
	v_lshlrev_b32_e32 v210, 2, v0
	v_ashrrev_i32_e32 v203, 31, v202
	v_sub_u32_e32 v211, v202, v178
	v_readlane_b32 s46, v254, 32
	s_mov_b32 s47, s4
	v_readlane_b32 s5, v253, 21
	s_mov_b32 s100, 0
	s_branch .LBB0_901

.LBB0_901:
	s_lshl_b32 s4, s47, 5
	s_and_b32 s50, s4, 0xfe0
	s_add_i32 s5, s50, 0x9f
	s_add_i32 s4, s50, 0xffffff80
	s_lshr_b32 s5, s5, 6
	s_bfe_u32 s48, s47, 0x40007
	s_ashr_i32 s49, s47, 11
	s_ashr_i32 s4, s4, 6
	s_add_i32 s5, s5, 1
	s_cmpk_lt_u32 s50, 0xf61
	s_cselect_b32 s51, s5, 64
	v_mov_b32_e32 v49, 0
	s_cmp_ge_i32 s4, s51
	v_mov_b32_e32 v48, 0
	v_mov_b32_e32 v47, 0
	v_mov_b32_e32 v46, 0
	v_mov_b32_e32 v45, 0
	v_mov_b32_e32 v44, 0
	v_mov_b32_e32 v43, 0
	v_mov_b32_e32 v42, 0
	v_mov_b32_e32 v41, 0
	v_mov_b32_e32 v40, 0
	v_mov_b32_e32 v39, 0
	v_mov_b32_e32 v38, 0
	v_mov_b32_e32 v37, 0
	v_mov_b32_e32 v36, 0
	v_mov_b32_e32 v35, 0
	v_mov_b32_e32 v34, 0
	v_mov_b32_e32 v65, 0
	v_mov_b32_e32 v64, 0
	v_mov_b32_e32 v63, 0
	v_mov_b32_e32 v62, 0
	v_mov_b32_e32 v61, 0
	v_mov_b32_e32 v60, 0
	v_mov_b32_e32 v59, 0
	v_mov_b32_e32 v58, 0
	v_mov_b32_e32 v57, 0
	v_mov_b32_e32 v56, 0
	v_mov_b32_e32 v55, 0
	v_mov_b32_e32 v54, 0
	v_mov_b32_e32 v53, 0
	v_mov_b32_e32 v52, 0
	v_mov_b32_e32 v51, 0
	v_mov_b32_e32 v50, 0
	v_mov_b32_e32 v214, v179
	s_cbranch_scc1 .LBB0_900
	s_and_b32 s5, s46, 0xfe0
	v_subrev_u32_e32 v212, s5, v211
	s_lshl_b32 s5, s49, 4
	s_or_b32 s6, s5, s48
	s_ashr_i32 s7, s6, 31
	s_lshl_b64 s[6:7], s[6:7], 12
	s_or_b32 s5, s6, s50
	v_mov_b32_e32 v1, s7
	v_or_b32_e32 v0, s5, v178
	s_lshr_b32 s5, s48, 2
	s_lshl_b32 s6, s49, 2
	v_lshlrev_b64 v[0:1], 7, v[0:1]
	s_or_b32 s6, s5, s6
	s_not_b32 s5, s48
	v_lshl_add_u64 v[0:1], v[180:181], 0, v[0:1]
	s_lshl_b32 s5, s5, 3
	s_cmp_eq_u32 s100, 0
	s_cbranch_scc0 .Lpf_q
	global_load_dwordx4 v[98:101], v[0:1], off
	global_load_dwordx4 v[102:105], v[0:1], off offset:32
	global_load_dwordx4 v[106:109], v[0:1], off offset:64
	global_load_dwordx4 v[110:113], v[0:1], off offset:96
.Lpf_q:
	v_cvt_f32_i32_e32 v0, s5
	s_ashr_i32 s7, s6, 31
	s_lshl_b64 s[6:7], s[6:7], 19
	v_lshl_add_u64 v[204:205], v[182:183], 0, s[6:7]
	v_mul_f32_e32 v1, 0x3d800000, v0
	v_cmp_gt_f32_e32 vcc, s8, v1
	v_lshl_add_u64 v[206:207], v[184:185], 0, s[6:7]
	s_and_b64 s[6:7], vcc, exec
	v_cndmask_b32_e32 v1, 0, v241, vcc
	v_fmac_f32_e32 v1, 0x3d800000, v0
	v_exp_f32_e32 v0, v1
	s_cselect_b32 s5, 0xffffffc0, 0
	s_mov_b64 s[6:7], s[58:59]
	s_mov_b32 s8, s65
	v_ldexp_f32 v0, v0, s5
	s_lshl_b32 s5, s48, 2
	v_mul_f32_e32 v4, 0x3fb8aa3b, v0
	v_mov_b32_e32 v0, s5
	s_mov_b32 s5, s64
	s_mov_b32 s9, s57
	v_readlane_b32 s52, v253, 2
	v_readlane_b32 s56, v253, 6
	v_readlane_b32 s57, v253, 7
	s_max_i32 s52, s4, 0
	s_lshl_b32 s16, s52, 13
	v_mov_b32_e32 v46, v33
	v_mov_b32_e32 v47, v33
	v_mov_b32_e32 v32, v33
	v_mov_b32_e32 v34, v33
	v_mov_b32_e32 v35, v33
	s_mov_b64 s[70:71], s[56:57]
	s_cmp_eq_u32 s100, 0
	s_cbranch_scc0 .Lpf_kv
	global_load_dword v0, v0, s[56:57]
	v_lshl_add_u64 v[6:7], v[204:205], 0, s[16:17]
	v_add_co_u32_e32 v8, vcc, s79, v6
	s_nop 1
	v_addc_co_u32_e32 v9, vcc, 0, v7, vcc
	global_load_dwordx4 v[114:117], v[8:9], off offset:3072
	global_load_dwordx4 v[118:121], v[8:9], off offset:2048
	global_load_dwordx4 v[122:125], v[8:9], off offset:1024
	global_load_dwordx4 v[126:129], v[8:9], off
	global_load_dwordx4 v[130:133], v[6:7], off offset:3072
	global_load_dwordx4 v[134:137], v[6:7], off offset:2048
	global_load_dwordx4 v[138:141], v[6:7], off offset:1024
	global_load_dwordx4 v[142:145], v[6:7], off
	v_lshl_add_u64 v[10:11], v[206:207], 0, s[16:17]
	global_load_dwordx4 v[174:177], v[10:11], off offset:-4096
	global_load_dwordx4 v[170:173], v[10:11], off offset:-3072
	global_load_dwordx4 v[166:169], v[10:11], off offset:-2048
	global_load_dwordx4 v[162:165], v[10:11], off offset:-1024
	global_load_dwordx4 v[158:161], v[10:11], off
	global_load_dwordx4 v[154:157], v[10:11], off offset:1024
	global_load_dwordx4 v[150:153], v[10:11], off offset:2048
	global_load_dwordx4 v[146:149], v[10:11], off offset:3072
.Lpf_kv:
	v_mov_b32_e32 v36, v33
	v_mov_b32_e32 v37, v33
	v_mov_b32_e32 v38, v33
	v_mov_b32_e32 v39, v33
	v_mov_b32_e32 v40, v33
	v_mov_b32_e32 v41, v33
	v_mov_b32_e32 v42, v33
	v_mov_b32_e32 v43, v33
	v_mov_b32_e32 v44, v33
	v_mov_b32_e32 v45, v33
	v_mov_b64_e32 v[64:65], v[46:47]
	v_readlane_b32 s53, v253, 3
	v_readlane_b32 s54, v253, 4
	v_readlane_b32 s55, v253, 5
	v_readlane_b32 s58, v253, 8
	v_readlane_b32 s59, v253, 9
	v_readlane_b32 s60, v253, 10
	v_readlane_b32 s61, v253, 11
	v_readlane_b32 s62, v253, 12
	v_readlane_b32 s63, v253, 13
	v_readlane_b32 s64, v253, 14
	v_readlane_b32 s65, v253, 15
	v_readlane_b32 s66, v253, 16
	v_readlane_b32 s67, v253, 17
	v_readfirstlane_b32 s38, v4
	v_mov_b64_e32 v[62:63], v[44:45]
	v_mov_b64_e32 v[60:61], v[42:43]
	v_mov_b64_e32 v[58:59], v[40:41]
	v_mov_b64_e32 v[56:57], v[38:39]
	v_mov_b64_e32 v[54:55], v[36:37]
	v_mov_b64_e32 v[52:53], v[34:35]
	v_mov_b64_e32 v[50:51], v[32:33]
	v_mov_b64_e32 v[48:49], v[46:47]
	s_mov_b32 s65, s8
	s_mov_b32 s64, s5
	s_mov_b64 s[58:59], s[6:7]
	s_mov_b32 s57, s9
	s_add_i32 s53, s50, 0x42
	s_add_i32 s54, s50, 0xffffff9e
	s_mov_b32 s39, s38
	s_mov_b32 s55, s38
	s_mov_b32 s80, s38
	s_mov_b32 s81, s38
	s_mov_b32 s82, s38
	s_mov_b32 s83, s38
	s_mov_b32 s84, s38
	s_mov_b32 s85, s38
	s_mov_b32 s86, s38
	s_mov_b32 s87, s38
	s_mov_b32 s88, s38
	s_mov_b32 s89, s38
	s_mov_b32 s93, s38
	s_mov_b32 s94, s38
	s_mov_b32 s95, s38
	s_mov_b32 s96, s38
	s_mov_b32 s97, s38
	s_mov_b32 s4, s38
	s_mov_b32 s5, s38
	s_mov_b32 s6, s38
	s_mov_b32 s7, s38
	s_mov_b32 s8, s38
	s_lshl_b32 s9, s52, 6
	s_mov_b64 s[40:41], s[16:17]
	v_mov_b64_e32 v[46:47], v[44:45]
	v_mov_b64_e32 v[44:45], v[42:43]
	v_mov_b64_e32 v[42:43], v[40:41]
	v_mov_b64_e32 v[40:41], v[38:39]
	v_mov_b64_e32 v[38:39], v[36:37]
	s_cmp_eq_u32 s100, 0
	s_cbranch_scc0 .Lpf_w
	s_waitcnt vmcnt(16)
	s_branch .Lpf_w2
.Lpf_w:
	s_waitcnt vmcnt(12)
	v_mov_b32_e32 v0, s101
	s_mov_b32 s100, 0
.Lpf_w2:
	v_mul_f32_e32 v213, 0x3fb8aa3b, v0
	v_mov_b64_e32 v[36:37], v[34:35]
	v_mov_b64_e32 v[34:35], v[32:33]
	v_mov_b32_e32 v214, v179
	s_add_i32 s4, s47, s58
	s_cmp_le_i32 s4, 0x3fff
	s_cselect_b32 s66, -1, 0
	s_lshl_b32 s5, s4, 5
	s_and_b32 s5, s5, 0xfe0
	s_bfe_u32 s6, s4, 0x40007
	s_ashr_i32 s7, s4, 11
	s_lshl_b32 s69, s6, 2
	s_lshl_b32 s8, s7, 4
	s_or_b32 s8, s8, s6
	s_lshl_b32 s8, s8, 12
	s_or_b32 s8, s8, s5
	s_lshl_b32 s62, s8, 7
	s_mov_b32 s63, 0
	s_lshr_b32 s6, s6, 2
	s_lshl_b32 s7, s7, 2
	s_or_b32 s6, s6, s7
	s_lshl_b32 s6, s6, 19
	s_add_i32 s5, s5, 0xffffff80
	s_ashr_i32 s5, s5, 6
	s_max_i32 s5, s5, 0
	s_lshl_b32 s5, s5, 13
	s_add_u32 s6, s6, s5
	s_lshr_b32 s7, s48, 2
	s_lshl_b32 s8, s49, 2
	s_or_b32 s7, s7, s8
	s_lshl_b32 s7, s7, 19
	s_sub_u32 s60, s6, s7
	s_subb_u32 s61, 0, 0
	s_mov_b32 s8, 0xc2fc0000
	s_branch .LBB0_904

.LBB0_904:
	s_waitcnt vmcnt(8)
	v_mfma_f32_32x32x16_bf16 v[66:81], v[142:145], v[98:101], 0
	s_mov_b32 s10, s52
	s_add_i32 s52, s52, 1
	s_cmp_ge_u32 s52, s51
	s_cselect_b64 s[42:43], -1, 0
	s_cmp_lt_u32 s52, s51
	v_mfma_f32_32x32x16_bf16 v[82:97], v[126:129], v[98:101], 0
	s_cselect_b32 s16, s52, s10
	s_lshl_b64 s[40:41], s[16:17], 13
	s_and_b32 s67, s42, s66
	s_cmp_lg_u32 s67, 0
	s_cselect_b32 s40, s60, s40
	s_cselect_b32 s41, s61, s41
	v_mfma_f32_32x32x16_bf16 v[66:81], v[138:141], v[102:105], v[66:81]
	v_lshl_add_u64 v[0:1], v[204:205], 0, s[40:41]
	global_load_dwordx4 v[142:145], v[0:1], off
	global_load_dwordx4 v[138:141], v[0:1], off offset:1024
	s_cmp_lt_u32 s9, s53
	s_cselect_b64 s[10:11], -1, 0
	s_cmp_gt_i32 s9, s54
	s_cselect_b64 s[44:45], -1, 0
	s_and_b64 s[10:11], s[10:11], s[44:45]
	v_mfma_f32_32x32x16_bf16 v[82:97], v[122:125], v[102:105], v[82:97]
	s_mov_b64 s[44:45], -1
	v_mfma_f32_32x32x16_bf16 v[66:81], v[134:137], v[106:109], v[66:81]
	v_mfma_f32_32x32x16_bf16 v[82:97], v[118:121], v[106:109], v[82:97]
	v_mfma_f32_32x32x16_bf16 v[66:81], v[130:133], v[110:113], v[66:81]
	global_load_dwordx4 v[134:137], v[0:1], off offset:2048
	global_load_dwordx4 v[130:133], v[0:1], off offset:3072
	v_add_co_u32_e32 v0, vcc, s79, v0
	s_nop 1
	v_addc_co_u32_e32 v1, vcc, 0, v1, vcc
	global_load_dwordx4 v[126:129], v[0:1], off
	global_load_dwordx4 v[122:125], v[0:1], off offset:1024
	v_mfma_f32_32x32x16_bf16 v[82:97], v[114:117], v[110:113], v[82:97]
	global_load_dwordx4 v[118:121], v[0:1], off offset:2048
	global_load_dwordx4 v[114:117], v[0:1], off offset:3072
	s_cmp_lg_u32 s67, 0
	s_cbranch_scc0 .Lpf_nq
	v_lshlrev_b32_e32 v16, 7, v178
	v_mov_b32_e32 v17, 0
	v_lshl_add_u64 v[16:17], v[180:181], 0, v[16:17]
	v_lshl_add_u64 v[16:17], v[16:17], 0, s[62:63]
	global_load_dwordx4 v[98:101], v[16:17], off
	global_load_dwordx4 v[102:105], v[16:17], off offset:32
	global_load_dwordx4 v[106:109], v[16:17], off offset:64
	global_load_dwordx4 v[110:113], v[16:17], off offset:96
	s_load_dword s101, s[70:71], s69
	s_mov_b32 s100, 1
.Lpf_nq:
	v_add_u32_e32 v0, s9, v212
	v_cvt_f32_i32_e32 v32, v0
	s_and_b64 vcc, exec, s[10:11]
	v_add_f32_e32 v215, 1.0, v32
	v_and_b32_e32 v208, 0x7fffffff, v32
	v_and_b32_e32 v209, 0x7fffffff, v215
	s_cbranch_vccnz .LBB0_906
	v_add_f32_e32 v1, 1.0, v32
	v_cmp_le_f32_e64 vcc, |v32|, s92
	v_cmp_le_f32_e64 s[10:11], |v1|, s92
	v_fma_f32 v0, s38, -|v32|, v66
	v_fma_f32 v1, s38, -|v1|, v67
	v_cndmask_b32_e32 v0, v242, v0, vcc
	v_cndmask_b32_e64 v1, v242, v1, s[10:11]
	v_add_f32_e32 v2, 2.0, v32
	v_add_f32_e32 v3, 0x40400000, v32
	v_cmp_le_f32_e64 vcc, |v2|, s92
	v_cmp_le_f32_e64 s[10:11], |v3|, s92
	v_fma_f32 v2, s38, -|v2|, v68
	v_fma_f32 v3, s38, -|v3|, v69
	v_cndmask_b32_e32 v2, v242, v2, vcc
	v_cndmask_b32_e64 v3, v242, v3, s[10:11]
	v_add_f32_e32 v4, 0x41000000, v32
	v_add_f32_e32 v5, 0x41100000, v32
	v_cmp_le_f32_e64 vcc, |v4|, s92
	v_cmp_le_f32_e64 s[10:11], |v5|, s92
	v_fma_f32 v4, s38, -|v4|, v70
	v_fma_f32 v5, s38, -|v5|, v71
	v_cndmask_b32_e32 v4, v242, v4, vcc
	v_cndmask_b32_e64 v5, v242, v5, s[10:11]
	v_add_f32_e32 v6, 0x41200000, v32
	v_add_f32_e32 v7, 0x41300000, v32
	v_cmp_le_f32_e64 vcc, |v6|, s92
	v_cmp_le_f32_e64 s[10:11], |v7|, s92
	v_fma_f32 v6, s38, -|v6|, v72
	v_fma_f32 v7, s38, -|v7|, v73
	v_cndmask_b32_e32 v6, v242, v6, vcc
	v_cndmask_b32_e64 v7, v242, v7, s[10:11]
	v_add_f32_e32 v8, 0x41800000, v32
	v_add_f32_e32 v9, 0x41880000, v32
	v_cmp_le_f32_e64 vcc, |v8|, s92
	v_cmp_le_f32_e64 s[10:11], |v9|, s92
	v_fma_f32 v8, s38, -|v8|, v74
	v_fma_f32 v9, s38, -|v9|, v75
	v_cndmask_b32_e32 v8, v242, v8, vcc
	v_cndmask_b32_e64 v9, v242, v9, s[10:11]
	v_add_f32_e32 v10, 0x41900000, v32
	v_add_f32_e32 v11, 0x41980000, v32
	v_cmp_le_f32_e64 vcc, |v10|, s92
	v_cmp_le_f32_e64 s[10:11], |v11|, s92
	v_fma_f32 v10, s38, -|v10|, v76
	v_fma_f32 v11, s38, -|v11|, v77
	v_cndmask_b32_e32 v10, v242, v10, vcc
	v_cndmask_b32_e64 v11, v242, v11, s[10:11]
	v_add_f32_e32 v12, 0x41c00000, v32
	v_add_f32_e32 v13, 0x41c80000, v32
	v_cmp_le_f32_e64 vcc, |v12|, s92
	v_cmp_le_f32_e64 s[10:11], |v13|, s92
	v_fma_f32 v12, s38, -|v12|, v78
	v_fma_f32 v13, s38, -|v13|, v79
	v_cndmask_b32_e32 v12, v242, v12, vcc
	v_cndmask_b32_e64 v13, v242, v13, s[10:11]
	v_add_f32_e32 v14, 0x41d00000, v32
	v_add_f32_e32 v15, 0x41d80000, v32
	v_cmp_le_f32_e64 vcc, |v14|, s92
	v_cmp_le_f32_e64 s[10:11], |v15|, s92
	v_fma_f32 v14, s38, -|v14|, v80
	v_fma_f32 v15, s38, -|v15|, v81
	v_cndmask_b32_e32 v14, v242, v14, vcc
	v_cndmask_b32_e64 v15, v242, v15, s[10:11]
	v_add_f32_e32 v16, 0x42000000, v32
	v_add_f32_e32 v17, 0x42040000, v32
	v_cmp_le_f32_e64 vcc, |v16|, s92
	v_cmp_le_f32_e64 s[10:11], |v17|, s92
	v_fma_f32 v16, s38, -|v16|, v82
	v_fma_f32 v17, s38, -|v17|, v83
	v_cndmask_b32_e32 v16, v242, v16, vcc
	v_cndmask_b32_e64 v17, v242, v17, s[10:11]
	v_add_f32_e32 v18, 0x42080000, v32
	v_add_f32_e32 v19, 0x420c0000, v32
	v_cmp_le_f32_e64 vcc, |v18|, s92
	v_cmp_le_f32_e64 s[10:11], |v19|, s92
	v_fma_f32 v18, s38, -|v18|, v84
	v_fma_f32 v19, s38, -|v19|, v85
	v_cndmask_b32_e32 v18, v242, v18, vcc
	v_cndmask_b32_e64 v19, v242, v19, s[10:11]
	v_add_f32_e32 v20, 0x42200000, v32
	v_add_f32_e32 v21, 0x42240000, v32
	v_cmp_le_f32_e64 vcc, |v20|, s92
	v_cmp_le_f32_e64 s[10:11], |v21|, s92
	v_fma_f32 v20, s38, -|v20|, v86
	v_fma_f32 v21, s38, -|v21|, v87
	v_cndmask_b32_e32 v20, v242, v20, vcc
	v_cndmask_b32_e64 v21, v242, v21, s[10:11]
	v_add_f32_e32 v22, 0x42280000, v32
	v_add_f32_e32 v23, 0x422c0000, v32
	v_cmp_le_f32_e64 vcc, |v22|, s92
	v_cmp_le_f32_e64 s[10:11], |v23|, s92
	v_fma_f32 v22, s38, -|v22|, v88
	v_fma_f32 v23, s38, -|v23|, v89
	v_cndmask_b32_e32 v22, v242, v22, vcc
	v_cndmask_b32_e64 v23, v242, v23, s[10:11]
	v_add_f32_e32 v24, 0x42400000, v32
	v_add_f32_e32 v25, 0x42440000, v32
	v_cmp_le_f32_e64 vcc, |v24|, s92
	v_cmp_le_f32_e64 s[10:11], |v25|, s92
	v_fma_f32 v24, s38, -|v24|, v90
	v_fma_f32 v25, s38, -|v25|, v91
	v_cndmask_b32_e32 v24, v242, v24, vcc
	v_cndmask_b32_e64 v25, v242, v25, s[10:11]
	v_add_f32_e32 v26, 0x42480000, v32
	v_add_f32_e32 v27, 0x424c0000, v32
	v_cmp_le_f32_e64 vcc, |v26|, s92
	v_cmp_le_f32_e64 s[10:11], |v27|, s92
	v_fma_f32 v26, s38, -|v26|, v92
	v_fma_f32 v27, s38, -|v27|, v93
	v_cndmask_b32_e32 v26, v242, v26, vcc
	v_cndmask_b32_e64 v27, v242, v27, s[10:11]
	v_add_f32_e32 v28, 0x42600000, v32
	v_add_f32_e32 v29, 0x42640000, v32
	v_cmp_le_f32_e64 vcc, |v28|, s92
	v_cmp_le_f32_e64 s[10:11], |v29|, s92
	v_fma_f32 v28, s38, -|v28|, v94
	v_fma_f32 v29, s38, -|v29|, v95
	v_cndmask_b32_e32 v28, v242, v28, vcc
	v_cndmask_b32_e64 v29, v242, v29, s[10:11]
	v_add_f32_e32 v30, 0x42680000, v32
	v_add_f32_e32 v31, 0x426c0000, v32
	v_cmp_le_f32_e64 vcc, |v30|, s92
	v_cmp_le_f32_e64 s[10:11], |v31|, s92
	v_fma_f32 v30, s38, -|v30|, v96
	v_fma_f32 v31, s38, -|v31|, v97
	v_cndmask_b32_e32 v30, v242, v30, vcc
	v_cndmask_b32_e64 v31, v242, v31, s[10:11]
	s_mov_b64 s[44:45], 0
